# grid barrier tail rewritten: all workgroups poll the top arrival counter (TOP >= (gen+1)*nx); XCD-last arriver releases and bumps TOP without a returning atomic; TOPGEN/XGEN hops removed
# speedup vs baseline: 1.0062x; 1.0043x over previous
.LBB0_1347:
	s_or_b64 exec, exec, s[6:7]
	v_cvt_f32_u32_e32 v5, v3
	s_waitcnt vmcnt(0)
	v_readfirstlane_b32 s4, v4
	v_sub_u32_e32 v4, 0, v3
	v_rcp_iflag_f32_e32 v5, v5
	v_add_u32_e32 v6, s4, v1
	v_mul_f32_e32 v5, 0x4f7ffffe, v5
	v_cvt_u32_f32_e32 v5, v5
	v_mul_lo_u32 v1, v4, v5
	v_mul_hi_u32 v1, v5, v1
	v_add_u32_e32 v1, v5, v1
	v_mul_hi_u32 v1, v6, v1
	v_mul_lo_u32 v4, v1, v3
	v_sub_u32_e32 v4, v6, v4
	v_add_u32_e32 v5, 1, v1
	v_cmp_ge_u32_e32 vcc, v4, v3
	s_nop 1
	v_cndmask_b32_e32 v1, v1, v5, vcc
	v_sub_u32_e32 v5, v4, v3
	v_cndmask_b32_e32 v4, v4, v5, vcc
	v_add_u32_e32 v5, 1, v1
	v_cmp_ge_u32_e32 vcc, v4, v3
	v_add_u32_e32 v4, 1, v6
	s_nop 0
	v_cndmask_b32_e32 v1, v1, v5, vcc
	v_mul_lo_u32 v5, v3, v1
	v_add_u32_e32 v3, v5, v3
	v_cmp_ne_u32_e32 vcc, v4, v3
	s_waitcnt lgkmcnt(0)
	v_add_u32_e32 v5, 1, v1
	v_mul_lo_u32 v5, v5, v2
	v_readlane_b32 s8, v254, 6
	v_readlane_b32 s9, v254, 7
	s_nop 4
	s_cbranch_vccnz .Lbar_wait
	buffer_wbl2 sc1
	s_waitcnt vmcnt(0)
	global_atomic_add v26, v228, s[8:9]
.Lbar_wait:
	s_mov_b32 s24, 0
.Lbar_spin:
	global_load_dword v4, v26, s[8:9] sc1
	s_add_i32 s24, s24, 1
	s_waitcnt vmcnt(0)
	v_cmp_ge_u32_e32 vcc, v4, v5
	s_cbranch_vccnz .Lbar_done
	s_and_b32 s10, s24, 0xff
	s_cmp_lg_u32 s10, 0
	s_cbranch_scc1 .Lbar_spin
	global_load_dword v4, v26, s[60:61] sc1
	s_waitcnt vmcnt(0)
	v_cmp_ne_u32_e32 vcc, 0, v4
	s_cbranch_vccnz .Lbar_done
	s_cmp_lt_u32 s24, 0x100001
	s_cbranch_scc1 .Lbar_spin
	global_atomic_add v26, v228, s[60:61]
.Lbar_done:
	s_waitcnt vmcnt(0)
	buffer_inv sc1
	s_waitcnt vmcnt(0)
	s_branch .LBB0_1383

.LBB0_1375:
	s_branch .LBB0_794
.LBB0_1383:
	s_or_b64 exec, exec, s[0:1]
	s_waitcnt lgkmcnt(0)
	s_barrier
